# speedup vs baseline: 1.0625x; 1.0008x over previous
.Lscan_top_done:
	s_or_b32 s69, s62, 0x26400
	s_waitcnt lgkmcnt(0)
	s_barrier
	v_lshl_add_u32 v46, v143, 2, s69
	ds_read_b128 v[216:219], v46 offset:1024
	ds_read_b128 v[220:223], v46 offset:1040
	s_add_i32 s82, s94, 1
	s_cmp_ge_u32 s82, s66
	s_cselect_b64 s[62:63], -1, 0
	s_and_b64 vcc, exec, s[62:63]
	s_waitcnt lgkmcnt(0)
	v_lshlrev_b32_e32 v224, 16, v58
	v_and_b32_e32 v225, 0xffff0000, v58
	v_lshlrev_b32_e32 v226, 16, v59
	v_and_b32_e32 v227, 0xffff0000, v59
	v_lshlrev_b32_e32 v228, 16, v60
	v_and_b32_e32 v229, 0xffff0000, v60
	v_lshlrev_b32_e32 v230, 16, v61
	v_and_b32_e32 v231, 0xffff0000, v61
	v_pk_mul_f32 v[224:225], v[224:225], v[216:217]
	v_pk_mul_f32 v[226:227], v[226:227], v[218:219]
	v_pk_mul_f32 v[228:229], v[228:229], v[220:221]
	v_pk_mul_f32 v[230:231], v[230:231], v[222:223]
	v_cvt_pk_bf16_f32 v232, v224, v225
	v_cvt_pk_bf16_f32 v233, v226, v227
	v_cvt_pk_bf16_f32 v234, v228, v229
	v_cvt_pk_bf16_f32 v235, v230, v231
	v_add_u32_e32 v38, v149, v147
	ds_write_b128 v38, v[232:235]
	v_lshlrev_b32_e32 v224, 16, v70
	v_and_b32_e32 v225, 0xffff0000, v70
	v_lshlrev_b32_e32 v226, 16, v71
	v_and_b32_e32 v227, 0xffff0000, v71
	v_lshlrev_b32_e32 v228, 16, v72
	v_and_b32_e32 v229, 0xffff0000, v72
	v_lshlrev_b32_e32 v230, 16, v73
	v_and_b32_e32 v231, 0xffff0000, v73
	v_pk_mul_f32 v[224:225], v[224:225], v[216:217]
	v_pk_mul_f32 v[226:227], v[226:227], v[218:219]
	v_pk_mul_f32 v[228:229], v[228:229], v[220:221]
	v_pk_mul_f32 v[230:231], v[230:231], v[222:223]
	v_cvt_pk_bf16_f32 v236, v224, v225
	v_cvt_pk_bf16_f32 v237, v226, v227
	v_cvt_pk_bf16_f32 v238, v228, v229
	v_cvt_pk_bf16_f32 v239, v230, v231
	ds_write_b128 v172, v[236:239]
	v_lshlrev_b32_e32 v224, 16, v82
	v_and_b32_e32 v225, 0xffff0000, v82
	v_lshlrev_b32_e32 v226, 16, v83
	v_and_b32_e32 v227, 0xffff0000, v83
	v_lshlrev_b32_e32 v228, 16, v84
	v_and_b32_e32 v229, 0xffff0000, v84
	v_lshlrev_b32_e32 v230, 16, v85
	v_and_b32_e32 v231, 0xffff0000, v85
	v_pk_mul_f32 v[224:225], v[224:225], v[216:217]
	v_pk_mul_f32 v[226:227], v[226:227], v[218:219]
	v_pk_mul_f32 v[228:229], v[228:229], v[220:221]
	v_pk_mul_f32 v[230:231], v[230:231], v[222:223]
	v_cvt_pk_bf16_f32 v240, v224, v225
	v_cvt_pk_bf16_f32 v241, v226, v227
	v_cvt_pk_bf16_f32 v242, v228, v229
	v_cvt_pk_bf16_f32 v243, v230, v231
	ds_write_b128 v172, v[240:243] offset:9216
	v_lshlrev_b32_e32 v224, 16, v94
	v_and_b32_e32 v225, 0xffff0000, v94
	v_lshlrev_b32_e32 v226, 16, v95
	v_and_b32_e32 v227, 0xffff0000, v95
	v_lshlrev_b32_e32 v228, 16, v96
	v_and_b32_e32 v229, 0xffff0000, v96
	v_lshlrev_b32_e32 v230, 16, v97
	v_and_b32_e32 v231, 0xffff0000, v97
	v_pk_mul_f32 v[224:225], v[224:225], v[216:217]
	v_pk_mul_f32 v[226:227], v[226:227], v[218:219]
	v_pk_mul_f32 v[228:229], v[228:229], v[220:221]
	v_pk_mul_f32 v[230:231], v[230:231], v[222:223]
	v_cvt_pk_bf16_f32 v244, v224, v225
	v_cvt_pk_bf16_f32 v245, v226, v227
	v_cvt_pk_bf16_f32 v246, v228, v229
	v_cvt_pk_bf16_f32 v247, v230, v231
	ds_write_b128 v172, v[244:247] offset:18432
	s_cbranch_vccnz .LBB0_608
	s_lshl_b64 s[70:71], s[82:83], 17
	s_add_u32 s76, s88, s70
	s_addc_u32 s77, s89, s71
	s_add_u32 s70, s90, s70
	s_addc_u32 s71, s91, s71
	s_lshl_b32 s78, s82, 7
	s_add_u32 vcc_lo, s92, s78
	v_lshl_add_u64 v[34:35], s[76:77], 0, v[104:105]
	s_addc_u32 vcc_hi, s93, 0
	global_load_dwordx4 v[50:53], v[34:35], off
	v_lshl_add_u64 v[34:35], s[70:71], 0, v[104:105]
	global_load_dwordx4 v[54:57], v[34:35], off
	v_lshl_add_u64 v[34:35], v[0:1], 1, vcc
	global_load_dwordx4 v[58:61], v[34:35], off
	v_lshl_add_u64 v[34:35], s[76:77], 0, v[106:107]
	global_load_dwordx4 v[62:65], v[34:35], off
	v_lshl_add_u64 v[34:35], s[70:71], 0, v[106:107]
	global_load_dwordx4 v[66:69], v[34:35], off
	v_lshl_add_u64 v[34:35], v[108:109], 1, vcc
	global_load_dwordx4 v[70:73], v[34:35], off
	v_lshl_add_u64 v[34:35], s[76:77], 0, v[110:111]
	global_load_dwordx4 v[74:77], v[34:35], off
	v_lshl_add_u64 v[34:35], s[70:71], 0, v[110:111]
	global_load_dwordx4 v[78:81], v[34:35], off
	v_lshl_add_u64 v[34:35], v[112:113], 1, vcc
	global_load_dwordx4 v[82:85], v[34:35], off
	v_lshl_add_u64 v[34:35], s[76:77], 0, v[114:115]
	global_load_dwordx4 v[86:89], v[34:35], off
	v_lshl_add_u64 v[34:35], s[70:71], 0, v[114:115]
	s_mov_b32 s79, s83
	global_load_dwordx4 v[90:93], v[34:35], off
	v_lshl_add_u64 v[34:35], v[116:117], 1, vcc
	global_load_dwordx4 v[94:97], v[34:35], off
	v_lshl_add_u64 v[34:35], v[118:119], 0, s[78:79]
	global_load_dwordx4 v[98:101], v[34:35], off nt
	s_and_saveexec_b64 s[76:77], s[8:9]
	s_cbranch_execz .LBB0_607
	s_lshl_b32 s70, s82, 6
	s_add_i32 s70, s70, s86
	s_ashr_i32 s71, s70, 31
	s_lshl_b64 s[70:71], s[70:71], 5
	v_lshl_add_u64 v[34:35], v[120:121], 0, s[70:71]
	global_load_dword v144, v[34:35], off
	global_load_dword v145, v[34:35], off offset:16
